# XCD-scoped synchronization: the three seams whose producer and consumer rows are XCD-local (out-proj0|rmsnorm, rmsnorm|in-proj1, out-proj1|final rmsnorm) use a per-XCD counter barrier without L2 write
# speedup vs baseline: 1.0030x; 1.0030x over previous
;   DI unsigned* bar() const { return (unsigned*)(ws + OFF_BAR); }
; #define LAS __attribute__((address_space(3)))
; __device__ __forceinline__ unsigned xb_add(unsigned* p, unsigned v) { return __hip_atomic_fetch_add(p, v, __ATOMIC_RELAXED, __HIP_MEMORY_SCOPE_AGENT); }
; __device__ __forceinline__ unsigned xb_xcc_id() { return (unsigned)__builtin_amdgcn_s_getreg((3 << 11) | 20) & 0xFu; }
; __device__ __forceinline__ XcdBarrier xcd_barrier_post(unsigned* bar, volatile LAS unsigned* st) {
;     XcdBarrier b; b.bar = bar; b.x = xb_xcc_id(); b.st = st;
;     if (threadIdx.x == 0) (void)xb_add(&bar[XB_XCNT(b.x)], 1u);
;     return b;
; }
.Lgs_149:
	v_readlane_b32 s98, v252, 1
	s_and_b32 s99, s84, 7
	s_cmp_lg_u32 s98, s99
	s_cbranch_scc1 .Lxl_setflag
	s_cmp_eq_u32 s96, 0x100
	s_cbranch_scc1 .Lxl_flagok
.Lxl_setflag:
	v_mov_b32_e32 v6, 0
	v_mov_b32_e32 v7, 1
	global_atomic_or v6, v7, s[94:95] offset:256
	s_waitcnt vmcnt(0)

; DI void gbar(unsigned* ctr, unsigned& epoch) {
;   asm volatile("s_waitcnt vmcnt(0)" ::: "memory");
;   __syncthreads();
;   if (threadIdx.x == 0) {
;     __builtin_amdgcn_fence(__ATOMIC_RELEASE, "agent");
;     asm volatile("s_waitcnt vmcnt(0)" ::: "memory");
;     __hip_atomic_fetch_add(ctr, 1u, __ATOMIC_RELAXED, __HIP_MEMORY_SCOPE_AGENT);
;     const unsigned target = (epoch + 1u) * gridDim.x;
;     while (__hip_atomic_load(ctr, __ATOMIC_RELAXED, __HIP_MEMORY_SCOPE_AGENT) < target) __builtin_amdgcn_s_sleep(2);
;     __builtin_amdgcn_fence(__ATOMIC_ACQUIRE, "agent");
;     asm volatile("s_waitcnt vmcnt(0)" ::: "memory");
;   }
;   __syncthreads();
;   ++epoch;
; }
.LBB0_783:
	v_mov_b32_e32 v6, 0
	global_load_dword v7, v6, s[94:95] offset:256 sc1
	v_readlane_b32 s98, v252, 1
	s_lshl_b32 s98, s98, 8
	s_add_u32 s98, s94, s98
	s_addc_u32 s99, s95, 0
	s_waitcnt vmcnt(0) lgkmcnt(0)
	v_cmp_ne_u32_e32 vcc, 0, v7
	s_cbranch_vccnz .Lxl_full_1
	v_mov_b32_e32 v7, 1
	global_atomic_add v6, v7, s[98:99] offset:1088
	v_mul_u32_u24_e32 v8, 1, v2
	s_mov_b32 s100, 0
.Lxl_spin_1:
	s_sleep 1
	global_load_dword v7, v6, s[98:99] offset:1088 sc1
	s_add_i32 s100, s100, 1
	s_waitcnt vmcnt(0)
	v_cmp_ge_u32_e32 vcc, v7, v8
	s_cbranch_vccnz .Lxl_done_1
	s_cmp_lt_u32 s100, 0x4000
	s_cbranch_scc1 .Lxl_spin_1
.Lxl_done_1:
	buffer_inv sc1
	s_waitcnt vmcnt(0)
	s_branch .LBB0_819

;   DI unsigned* bar() const { return (unsigned*)(ws + OFF_BAR); }
; __device__ __forceinline__ unsigned xb_ld(unsigned* p)              { return __hip_atomic_load(p, __ATOMIC_RELAXED, __HIP_MEMORY_SCOPE_AGENT); }
; __device__ __forceinline__ unsigned xb_add(unsigned* p, unsigned v) { return __hip_atomic_fetch_add(p, v, __ATOMIC_RELAXED, __HIP_MEMORY_SCOPE_AGENT); }
; #define XB_SPIN(cond, bar) do { unsigned _sp = 0; while (cond) { __builtin_amdgcn_s_sleep(1); \
;     if ((++_sp & 255u) == 0u) { if (xb_ld(&(bar)[XB_TMO])) break; if (_sp > XB_SPIN_CAP) { atomicAdd(&(bar)[XB_TMO], 1u); break; } } } } while (0)
; __device__ __forceinline__ void xcd_barrier(const XcdBarrier& b) {
;     asm volatile("s_waitcnt vmcnt(0)" ::: "memory");
;     __syncthreads();
;     if (threadIdx.x == 0) {
;         unsigned* bar = b.bar;
;         __builtin_amdgcn_s_waitcnt(0);
;         unsigned nloc = b.st[0], nx = b.st[1];
;         if (nloc == 0u) { xcd_barrier_complete(bar, b.x, nloc, nx); b.st[0] = nloc; b.st[1] = nx; }
;         const unsigned old = xb_add(&bar[XB_XSUB(b.x)], 1u);
;         const unsigned gen = old / nloc;
;         if (old + 1u == (gen + 1u) * nloc) {
;             __builtin_amdgcn_fence(__ATOMIC_RELEASE, "agent");
;             asm volatile("s_waitcnt vmcnt(0)" ::: "memory");
;             const unsigned og = xb_add(&bar[XB_TOP], 1u);
;             const unsigned tg = og / nx;
;             if (og + 1u == (tg + 1u) * nx) xb_add(&bar[XB_TOPGEN], 1u);
;             else XB_SPIN(xb_ld(&bar[XB_TOPGEN]) == tg, bar);
;             __builtin_amdgcn_fence(__ATOMIC_ACQUIRE, "agent");
;             xb_add(&bar[XB_XGEN(b.x)], 1u);
;             asm volatile("s_waitcnt vmcnt(0)" ::: "memory");
;         } else {
;             XB_SPIN(xb_ld(&bar[XB_XGEN(b.x)]) == gen, bar);
;             __builtin_amdgcn_fence(__ATOMIC_ACQUIRE, "agent");
;             asm volatile("s_waitcnt vmcnt(0)" ::: "memory");
;         }
.LBB0_838:
	v_mov_b32_e32 v6, 0
	global_load_dword v7, v6, s[94:95] offset:256 sc1
	v_readlane_b32 s98, v252, 1
	s_lshl_b32 s98, s98, 8
	s_add_u32 s98, s94, s98
	s_addc_u32 s99, s95, 0
	s_waitcnt vmcnt(0) lgkmcnt(0)
	v_cmp_ne_u32_e32 vcc, 0, v7
	s_cbranch_vccnz .Lxl_full_2
	v_mov_b32_e32 v7, 1
	global_atomic_add v6, v7, s[98:99] offset:1088
	v_mul_u32_u24_e32 v8, 2, v2
	s_mov_b32 s100, 0

;   DI unsigned* bar() const { return (unsigned*)(ws + OFF_BAR); }
; __device__ __forceinline__ unsigned xb_ld(unsigned* p)              { return __hip_atomic_load(p, __ATOMIC_RELAXED, __HIP_MEMORY_SCOPE_AGENT); }
; __device__ __forceinline__ unsigned xb_add(unsigned* p, unsigned v) { return __hip_atomic_fetch_add(p, v, __ATOMIC_RELAXED, __HIP_MEMORY_SCOPE_AGENT); }
; #define XB_SPIN(cond, bar) do { unsigned _sp = 0; while (cond) { __builtin_amdgcn_s_sleep(1); \
;     if ((++_sp & 255u) == 0u) { if (xb_ld(&(bar)[XB_TMO])) break; if (_sp > XB_SPIN_CAP) { atomicAdd(&(bar)[XB_TMO], 1u); break; } } } } while (0)
; __device__ __forceinline__ void xcd_barrier(const XcdBarrier& b) {
;     asm volatile("s_waitcnt vmcnt(0)" ::: "memory");
;     __syncthreads();
;     if (threadIdx.x == 0) {
;         unsigned* bar = b.bar;
;         __builtin_amdgcn_s_waitcnt(0);
;         unsigned nloc = b.st[0], nx = b.st[1];
;         if (nloc == 0u) { xcd_barrier_complete(bar, b.x, nloc, nx); b.st[0] = nloc; b.st[1] = nx; }
;         const unsigned old = xb_add(&bar[XB_XSUB(b.x)], 1u);
;         const unsigned gen = old / nloc;
;         if (old + 1u == (gen + 1u) * nloc) {
;             __builtin_amdgcn_fence(__ATOMIC_RELEASE, "agent");
;             asm volatile("s_waitcnt vmcnt(0)" ::: "memory");
;             const unsigned og = xb_add(&bar[XB_TOP], 1u);
;             const unsigned tg = og / nx;
;             if (og + 1u == (tg + 1u) * nx) xb_add(&bar[XB_TOPGEN], 1u);
;             else XB_SPIN(xb_ld(&bar[XB_TOPGEN]) == tg, bar);
;             __builtin_amdgcn_fence(__ATOMIC_ACQUIRE, "agent");
;             xb_add(&bar[XB_XGEN(b.x)], 1u);
;             asm volatile("s_waitcnt vmcnt(0)" ::: "memory");
;         } else {
;             XB_SPIN(xb_ld(&bar[XB_XGEN(b.x)]) == gen, bar);
;             __builtin_amdgcn_fence(__ATOMIC_ACQUIRE, "agent");
;             asm volatile("s_waitcnt vmcnt(0)" ::: "memory");
;         }
.LBB0_1671:
	v_mov_b32_e32 v6, 0
	global_load_dword v7, v6, s[94:95] offset:256 sc1
	v_readlane_b32 s98, v252, 1
	s_lshl_b32 s98, s98, 8
	s_add_u32 s98, s94, s98
	s_addc_u32 s99, s95, 0
	s_waitcnt vmcnt(0) lgkmcnt(0)
	v_cmp_ne_u32_e32 vcc, 0, v7
	s_cbranch_vccnz .Lxl_full_3
	v_mov_b32_e32 v7, 1
	global_atomic_add v6, v7, s[98:99] offset:1088
	v_mul_u32_u24_e32 v8, 3, v2
	s_mov_b32 s100, 0
